# P3 chunk MLP units spread wave-major over workgroups 32-223 (5-6 per workgroup instead of 8 on 32-159)
# baseline (speedup 1.0000x reference)
; #define LAS __attribute__((address_space(3)))
; #define LDS_WAIT() asm volatile("s_waitcnt lgkmcnt(0)" ::: "memory")
; __device__ __forceinline__ void phase_chunk_mlp(const Params& P, const Ctx& C, int vb, int vn) {
;     ...
;     for (int un = vb * NWAVES + wave; un < 2 * 64 * 8; un += vn * NWAVES) {
;         const int g = un & 7, ch = (un >> 3) & 63, b = un >> 9;
;         const size_t row0 = (size_t)b * SEQ + ch * 128;
;         LDS_WAIT();
;         { u32x4 x[16]; const unsigned char* vsrc = (const unsigned char*)(V + (row0 + (lane >> 3)) * 512 + g * 64) + (lane & 7) * 16;
; #pragma unroll
;           for (int it = 0; it < 16; ++it) x[it] = *(const u32x4*)(vsrc + (size_t)(8 * it) * 1024);
; #pragma unroll
;           for (int it = 0; it < 16; ++it) *(LAS u32x4*)(vt + ((lane & 7) >> 2) * 8192 + (8 * it + (lane >> 3)) * 64 + (lane & 3) * 16) = x[it]; }
;         LDS_WAIT();
;         const LAS unsigned char* vb0 = vt + ((lane >> 4) & 1) * 32 + (lane & 3) * 8 + (8 * hi + ((lane & 15) >> 2)) * 64;
; #pragma unroll
;         for (int tb = 0; tb < 4; ++tb) {
;             const int t = 32 * tb + r32;
;             const bf16_t* wrow = SW + ((size_t)g * 128 + t) * 128 + 8 * hi;
;             bf16x8 wf[8];
; #pragma unroll
;             for (int ks = 0; ks < 2 * tb + 2; ++ks) wf[ks] = *(const bf16x8*)(wrow + 16 * ks);
;             const float bs = P.in[18][g * 128 + t];
;             const size_t ro = row0 + t;
;             u32x2 ug0[4], ug1[4];
; #pragma unroll
;             for (int rq = 0; rq < 4; ++rq) { const int d0 = 8 * rq + 4 * hi; ug0[rq] = *(const u32x2*)(U + ro * 512 + g * 64 + d0); ug1[rq] = *(const u32x2*)(U + ro * 512 + g * 64 + 32 + d0); }
.Lmy_t:
	s_cmp_lt_i32 s87, 32
	s_cbranch_scc1 .LBB0_1126
	s_load_dwordx2 s[12:13], s[90:91], 0x108
	s_sub_i32 s6, s87, 32
	s_sub_i32 s1, s68, 32
	s_waitcnt lgkmcnt(0)
	s_add_u32 s2, s12, 0x4a00000
	s_addc_u32 s3, s13, 0
	s_add_u32 s10, s12, 0x7d00000
	s_addc_u32 s11, s13, 0
	s_lshl_b32 s4, s6, 3
	v_readlane_b32 s14, v254, 6
	s_add_i32 s7, s14, s4
	s_cmpk_lg_i32 s68, 0x100
	s_cbranch_scc1 .Lmy_c1
	s_mul_i32 s7, s14, 0xc0
	s_add_i32 s7, s7, s6
	s_cmpk_lt_u32 s6, 0xc0
	s_cselect_b32 s7, s7, 0x400
.Lmy_c1:
	s_cmpk_gt_i32 s7, 0x3ff
	v_readlane_b32 s15, v254, 7
	v_mbcnt_lo_u32_b32 v33, -1, 0
	v_mbcnt_hi_u32_b32 v33, -1, v33
	s_cbranch_scc1 .LBB0_1120
	v_readlane_b32 s4, v254, 6
	s_lshl_b32 s4, s4, 14
	v_ashrrev_i32_e32 v34, 3, v33
	v_lshlrev_b32_e32 v2, 11, v33
	s_add_i32 s4, s4, 0
	v_and_b32_e32 v2, 0x2000, v2
	v_lshlrev_b32_e32 v3, 6, v34
	v_add3_u32 v8, s4, v2, v3
	v_lshlrev_b32_e32 v2, 4, v33
	v_and_b32_e32 v9, 48, v2
	v_lshlrev_b32_e32 v2, 1, v33
	v_and_b32_e32 v2, 32, v2
	v_ashrrev_i32_e32 v4, 5, v33
	v_add_u32_e32 v3, s4, v2
	v_lshlrev_b32_e32 v2, 3, v33
	v_and_b32_e32 v5, 24, v2
	v_lshlrev_b32_e32 v2, 3, v4
	v_lshrrev_b32_e32 v6, 2, v33
	v_and_or_b32 v6, v6, 3, v2
	v_lshlrev_b32_e32 v6, 6, v6
	v_add3_u32 v41, v3, v5, v6
	v_ashrrev_i32_e32 v3, 31, v2
	v_readlane_b32 s4, v254, 0
	v_lshl_add_u64 v[2:3], v[2:3], 1, s[12:13]
	s_mov_b64 s[14:15], 0x1d10000
	s_and_b32 s4, s7, 7
	v_lshl_add_u64 v[2:3], v[2:3], 0, s[14:15]
	s_lshl_b32 s14, s1, 3
	s_lshl_b32 s15, s4, 7
	v_and_b32_e32 v0, 7, v33
	s_add_u32 s16, s12, s15
	v_lshlrev_b32_e32 v0, 4, v0
	v_mov_b32_e32 v1, 0
	s_addc_u32 s17, s13, 0
	v_lshl_add_u64 v[6:7], s[16:17], 0, v[0:1]
	s_mov_b64 s[16:17], 0x5b00000
	v_lshl_add_u64 v[36:37], v[6:7], 0, s[16:17]
	s_add_u32 s16, s2, s15
	s_addc_u32 s17, s3, 0
	s_add_u32 s18, s10, s15
	v_and_b32_e32 v32, 31, v33
	s_addc_u32 s19, s11, 0
	s_lshl_b32 s4, s4, 15
	v_lshl_or_b32 v0, v32, 8, s4
	v_or_b32_e32 v40, 32, v32
	s_load_dwordx2 s[20:21], s[90:91], 0x90
	v_lshl_add_u64 v[38:39], v[2:3], 0, v[0:1]
	v_lshl_or_b32 v0, v40, 8, s4
	v_or_b32_e32 v44, 64, v32
	v_lshl_add_u64 v[42:43], v[2:3], 0, v[0:1]
	v_lshl_or_b32 v0, v44, 8, s4
	v_or_b32_e32 v48, 0x60, v32
	v_lshlrev_b32_e32 v4, 2, v4
	v_or_b32_e32 v6, s15, v32
	v_lshl_add_u64 v[46:47], v[2:3], 0, v[0:1]
	v_lshl_or_b32 v0, v48, 8, s4
	v_ashrrev_i32_e32 v5, 31, v4
	v_lshl_add_u64 v[50:51], v[2:3], 0, v[0:1]
	v_lshlrev_b32_e32 v0, 2, v6
	s_waitcnt lgkmcnt(0)
	v_lshl_add_u64 v[52:53], s[20:21], 0, v[0:1]
	v_lshlrev_b64 v[0:1], 1, v[4:5]
	v_readlane_b32 s5, v254, 7
	v_lshl_add_u64 v[54:55], s[16:17], 0, v[0:1]
	s_lshl_b32 s16, s68, 7
	s_mov_b32 s5, 0
	v_ashrrev_i32_e32 v35, 31, v34
	v_lshl_add_u64 v[56:57], s[18:19], 0, v[0:1]
	s_lshl_b32 s15, s7, 4
	s_addk_i32 s16, 0xf000
	v_add_u32_e32 v45, v8, v9
